# P0 weight-transpose item loop rewritten by hand: next item's 32 loads in flight while the current tile is read back, packed and stored (same items, same LDS tile, same arithmetic)
# speedup vs baseline: 1.0072x; 1.0072x over previous
.LBB0_17:
	s_add_u32 s70, s28, 0x500000
	s_addc_u32 s71, s29, 0
	s_add_u32 s68, s28, 0x700000
	s_addc_u32 s69, s29, 0
	s_add_u32 s72, s28, 0x800000
	s_addc_u32 s73, s29, 0
	s_add_u32 s66, s28, 0x1800000
	s_addc_u32 s67, s29, 0
	s_add_u32 s64, s28, 0x2000000
	s_addc_u32 s65, s29, 0
	s_load_dwordx16 s[12:27], s[0:1], 0x40
	s_add_u32 s0, s28, 0x4c00000
	s_addc_u32 s1, s29, 0
	v_writelane_b32 v254, s0, 3
	v_and_b32_e32 v204, 63, v205
	s_nop 0
	v_writelane_b32 v254, s1, 4
	v_writelane_b32 v254, s33, 5
	s_lshr_b32 s33, s33, 6
	s_cmp_lt_i32 s30, 1
	s_cselect_b64 s[0:1], -1, 0
	s_cmp_gt_i32 s31, 0
	s_cselect_b64 s[4:5], -1, 0
	s_and_b64 s[74:75], s[0:1], s[4:5]
	s_andn2_b64 vcc, exec, s[74:75]
	s_cbranch_vccnz .LBB0_143
	s_lshl_b32 s0, s2, 3
	s_add_i32 s4, s33, s0
	s_lshl_b32 s6, s34, 3
	s_cmpk_gt_i32 s4, 0x5bbf
	s_cbranch_scc1 .LBB0_91
	s_waitcnt lgkmcnt(0)
	v_and_b32_e32 v0, 31, v204
	v_lshrrev_b32_e32 v1, 5, v204
	v_and_b32_e32 v2, 7, v204
	v_lshrrev_b32_e32 v3, 3, v204
	s_lshl_b32 s0, s33, 14
	v_mul_u32_u24_e32 v4, 33, v1
	v_add_u32_e32 v4, v4, v0
	v_lshl_add_u32 v4, v4, 2, s0
	v_mul_u32_u24_e32 v5, 0x108, v2
	v_add_u32_e32 v5, v5, v3
	v_lshl_add_u32 v5, v5, 2, s0
	v_lshlrev_b32_e32 v9, 5, v2
	s_mov_b32 s7, s4
	s_mov_b32 s87, 0
.Lp0t_top:
	s_cmp_lt_u32 s7, 3904
	s_cbranch_scc1 .Lp0t_k_in
	s_cmp_lt_u32 s7, 4288
	s_cbranch_scc1 .Lp0t_k_uq
	s_cmp_lt_u32 s7, 4544
	s_cbranch_scc1 .Lp0t_k_ukv
	s_cmp_lt_u32 s7, 6592
	s_cbranch_scc1 .Lp0t_k_out
	s_cmp_lt_u32 s7, 12224
	s_cbranch_scc1 .Lp0t_k_g
	s_cmp_lt_u32 s7, 17856
	s_cbranch_scc1 .Lp0t_k_u
	s_sub_u32 s8, s7, 17856
	s_lshr_b32 s9, s8, 6
	s_and_b32 s10, s8, 63
	s_lshl_b32 s10, s10, 5
	s_mov_b64 s[78:79], s[54:55]
	s_add_u32 s80, s28, 0x4c00000
	s_addc_u32 s81, s29, 0
	s_movk_i32 s11, 2048
	s_movk_i32 s60, 5632
	s_mov_b32 s63, 0
	s_mov_b32 s61, s10
	s_mov_b32 s62, 1
	s_branch .Lp0t_common
.Lp0t_k_uq:
	s_sub_u32 s8, s7, 3904
	s_mul_hi_u32 s9, s8, 0x5555556
	s_mul_i32 s0, s9, 48
	s_sub_u32 s10, s8, s0
	s_lshl_b32 s10, s10, 5
	s_mov_b64 s[78:79], s[44:45]
	s_mov_b64 s[80:81], s[70:71]
	s_movk_i32 s11, 1536
	s_movk_i32 s60, 512
	s_mov_b32 s63, 1
	s_mov_b64 s[82:83], s[42:43]
	s_mov_b32 s61, s10
	s_mov_b32 s62, 1
	s_mul_i32 s0, s10, 43691
	s_lshr_b32 s0, s0, 23
	s_mul_i32 s0, s0, 192
	s_sub_u32 s3, s10, s0
	s_cmp_lt_u32 s3, 128
	s_cbranch_scc1 .Lp0t_common
	s_bfe_u32 s3, s3, 0x10005
	s_add_u32 s61, s0, s3
	s_add_u32 s61, s61, 128
	s_mov_b32 s62, 2
	s_branch .Lp0t_common
.Lp0t_k_ukv:
	s_sub_u32 s8, s7, 4288
	s_lshr_b32 s9, s8, 6
	s_and_b32 s10, s8, 63
	s_lshl_b32 s10, s10, 5
	s_mov_b64 s[78:79], s[48:49]
	s_mov_b64 s[80:81], s[68:69]
	s_movk_i32 s11, 2048
	s_movk_i32 s60, 256
	s_mov_b32 s63, 1
	s_mov_b64 s[82:83], s[46:47]
	s_mov_b32 s61, s10
	s_mov_b32 s62, 1
	s_branch .Lp0t_common
.Lp0t_k_out:
	s_sub_u32 s8, s7, 4544
	s_lshr_b32 s9, s8, 6
	s_and_b32 s10, s8, 63
	s_lshl_b32 s10, s10, 5
	s_mov_b64 s[78:79], s[22:23]
	s_mov_b64 s[80:81], s[66:67]
	s_movk_i32 s11, 2048
	s_movk_i32 s60, 2048
	s_mov_b32 s63, 0
	s_mov_b32 s61, s10
	s_mov_b32 s62, 1
	s_branch .Lp0t_common
.Lp0t_k_g:
	s_sub_u32 s8, s7, 6592
	s_mul_hi_u32 s9, s8, 0x1745d18
	s_mul_i32 s0, s9, 176
	s_sub_u32 s10, s8, s0
	s_lshl_b32 s10, s10, 5
	s_mov_b64 s[78:79], s[26:27]
	s_mov_b64 s[80:81], s[64:65]
	s_movk_i32 s11, 5632
	s_movk_i32 s60, 2048
	s_mov_b32 s63, 0
	s_mov_b32 s61, s10
	s_mov_b32 s62, 1
	s_lshr_b32 s0, s10, 7
	s_lshl_b32 s0, s0, 8
	s_and_b32 s3, s10, 127
	s_add_u32 s61, s0, s3
	s_branch .Lp0t_common
.Lp0t_k_u:
	s_sub_u32 s8, s7, 12224
	s_mul_hi_u32 s9, s8, 0x1745d18
	s_mul_i32 s0, s9, 176
	s_sub_u32 s10, s8, s0
	s_lshl_b32 s10, s10, 5
	s_mov_b64 s[78:79], s[52:53]
	s_mov_b64 s[80:81], s[64:65]
	s_movk_i32 s11, 5632
	s_movk_i32 s60, 2048
	s_mov_b32 s63, 0
	s_mov_b32 s61, s10
	s_mov_b32 s62, 1
	s_lshr_b32 s0, s10, 7
	s_lshl_b32 s0, s0, 8
	s_and_b32 s3, s10, 127
	s_add_u32 s61, s0, s3
	s_add_u32 s61, s61, 128
	s_branch .Lp0t_common
.Lp0t_k_in:
	s_mov_b32 s8, s7
	s_mul_hi_u32 s9, s8, 0x2192e2a
	s_mul_i32 s0, s9, 122
	s_sub_u32 s10, s8, s0
	s_lshl_b32 s10, s10, 5
	s_mov_b64 s[78:79], s[40:41]
	s_mov_b64 s[80:81], s[72:73]
	s_movk_i32 s11, 3904
	s_movk_i32 s60, 2048
	s_mov_b32 s63, 0
	s_mov_b32 s61, s10
	s_mov_b32 s62, 1
	s_cmp_lt_u32 s10, 3840
	s_cbranch_scc1 .Lp0t_common
	s_bfe_u32 s0, s10, 0x10005
	s_add_u32 s61, s0, 3840
	s_mov_b32 s62, 2
.Lp0t_common:
	s_lshl_b32 s9, s9, 6
	s_mul_i32 s0, s9, s11
	s_add_u32 s0, s0, s10
	s_lshl_b32 s0, s0, 2
	s_add_u32 s76, s78, s0
	s_addc_u32 s77, s79, 0
	s_lshl_b32 s1, s11, 3
	s_lshl_b32 s3, s11, 2
	v_mul_u32_u24_e32 v6, s3, v1
	v_lshl_add_u32 v6, v0, 2, v6
	s_mul_i32 s0, s61, s60
	s_add_u32 s0, s0, s9
	s_lshl_b32 s0, s0, 1
	s_add_u32 s88, s80, s0
	s_addc_u32 s89, s81, 0
	s_mul_i32 s85, s62, s60
	s_lshl_b32 s84, s85, 4
	s_lshl_b32 s85, s85, 1
	v_mul_u32_u24_e32 v7, s85, v3
	v_lshl_add_u32 v7, v2, 4, v7
	s_cmp_eq_u32 s63, 0
	s_cbranch_scc1 .Lp0t_nog
	s_lshl_b32 s0, s9, 2
	s_add_u32 s82, s82, s0
	s_addc_u32 s83, s83, 0
	global_load_dwordx4 v[10:13], v9, s[82:83]
	global_load_dwordx4 v[14:17], v9, s[82:83] offset:16
.Lp0t_nog:
	global_load_dword v32, v6, s[76:77]
	s_add_u32 s76, s76, s1
	s_addc_u32 s77, s77, 0
	global_load_dword v33, v6, s[76:77]
	s_add_u32 s76, s76, s1
	s_addc_u32 s77, s77, 0
	global_load_dword v34, v6, s[76:77]
	s_add_u32 s76, s76, s1
	s_addc_u32 s77, s77, 0
	global_load_dword v35, v6, s[76:77]
	s_add_u32 s76, s76, s1
	s_addc_u32 s77, s77, 0
	global_load_dword v36, v6, s[76:77]
	s_add_u32 s76, s76, s1
	s_addc_u32 s77, s77, 0
	global_load_dword v37, v6, s[76:77]
	s_add_u32 s76, s76, s1
	s_addc_u32 s77, s77, 0
	global_load_dword v38, v6, s[76:77]
	s_add_u32 s76, s76, s1
	s_addc_u32 s77, s77, 0
	global_load_dword v39, v6, s[76:77]
	s_add_u32 s76, s76, s1
	s_addc_u32 s77, s77, 0
	global_load_dword v40, v6, s[76:77]
	s_add_u32 s76, s76, s1
	s_addc_u32 s77, s77, 0
	global_load_dword v41, v6, s[76:77]
	s_add_u32 s76, s76, s1
	s_addc_u32 s77, s77, 0
	global_load_dword v42, v6, s[76:77]
	s_add_u32 s76, s76, s1
	s_addc_u32 s77, s77, 0
	global_load_dword v43, v6, s[76:77]
	s_add_u32 s76, s76, s1
	s_addc_u32 s77, s77, 0
	global_load_dword v44, v6, s[76:77]
	s_add_u32 s76, s76, s1
	s_addc_u32 s77, s77, 0
	global_load_dword v45, v6, s[76:77]
	s_add_u32 s76, s76, s1
	s_addc_u32 s77, s77, 0
	global_load_dword v46, v6, s[76:77]
	s_add_u32 s76, s76, s1
	s_addc_u32 s77, s77, 0
	global_load_dword v47, v6, s[76:77]
	s_add_u32 s76, s76, s1
	s_addc_u32 s77, s77, 0
	global_load_dword v48, v6, s[76:77]
	s_add_u32 s76, s76, s1
	s_addc_u32 s77, s77, 0
	global_load_dword v49, v6, s[76:77]
	s_add_u32 s76, s76, s1
	s_addc_u32 s77, s77, 0
	global_load_dword v50, v6, s[76:77]
	s_add_u32 s76, s76, s1
	s_addc_u32 s77, s77, 0
	global_load_dword v51, v6, s[76:77]
	s_add_u32 s76, s76, s1
	s_addc_u32 s77, s77, 0
	global_load_dword v52, v6, s[76:77]
	s_add_u32 s76, s76, s1
	s_addc_u32 s77, s77, 0
	global_load_dword v53, v6, s[76:77]
	s_add_u32 s76, s76, s1
	s_addc_u32 s77, s77, 0
	global_load_dword v54, v6, s[76:77]
	s_add_u32 s76, s76, s1
	s_addc_u32 s77, s77, 0
	global_load_dword v55, v6, s[76:77]
	s_add_u32 s76, s76, s1
	s_addc_u32 s77, s77, 0
	global_load_dword v56, v6, s[76:77]
	s_add_u32 s76, s76, s1
	s_addc_u32 s77, s77, 0
	global_load_dword v57, v6, s[76:77]
	s_add_u32 s76, s76, s1
	s_addc_u32 s77, s77, 0
	global_load_dword v58, v6, s[76:77]
	s_add_u32 s76, s76, s1
	s_addc_u32 s77, s77, 0
	global_load_dword v59, v6, s[76:77]
	s_add_u32 s76, s76, s1
	s_addc_u32 s77, s77, 0
	global_load_dword v60, v6, s[76:77]
	s_add_u32 s76, s76, s1
	s_addc_u32 s77, s77, 0
	global_load_dword v61, v6, s[76:77]
	s_add_u32 s76, s76, s1
	s_addc_u32 s77, s77, 0
	global_load_dword v62, v6, s[76:77]
	s_add_u32 s76, s76, s1
	s_addc_u32 s77, s77, 0
	global_load_dword v63, v6, s[76:77]
	s_cmp_eq_u32 s87, 0
	s_cbranch_scc1 .Lp0t_first
	ds_read2_b32 v[64:65], v5 offset0:0 offset1:33
	ds_read2_b32 v[66:67], v5 offset0:66 offset1:99
	ds_read2_b32 v[68:69], v5 offset0:132 offset1:165
	ds_read2_b32 v[70:71], v5 offset0:198 offset1:231
	ds_read2_b32 v[72:73], v5 offset0:8 offset1:41
	ds_read2_b32 v[74:75], v5 offset0:74 offset1:107
	ds_read2_b32 v[76:77], v5 offset0:140 offset1:173
	ds_read2_b32 v[78:79], v5 offset0:206 offset1:239
	ds_read2_b32 v[80:81], v5 offset0:16 offset1:49
	ds_read2_b32 v[82:83], v5 offset0:82 offset1:115
	ds_read2_b32 v[84:85], v5 offset0:148 offset1:181
	ds_read2_b32 v[86:87], v5 offset0:214 offset1:247
	ds_read2_b32 v[88:89], v5 offset0:24 offset1:57
	ds_read2_b32 v[90:91], v5 offset0:90 offset1:123
	ds_read2_b32 v[92:93], v5 offset0:156 offset1:189
	ds_read2_b32 v[94:95], v5 offset0:222 offset1:255
	s_cmp_eq_u32 s93, 0
	s_waitcnt lgkmcnt(12)
	s_cbranch_scc1 .Lp0t_a_ng0
	v_mul_f32_e32 v64, v64, v18
	v_mul_f32_e32 v65, v65, v19
	v_mul_f32_e32 v66, v66, v20
	v_mul_f32_e32 v67, v67, v21
	v_mul_f32_e32 v68, v68, v22
	v_mul_f32_e32 v69, v69, v23
	v_mul_f32_e32 v70, v70, v24
	v_mul_f32_e32 v71, v71, v25
.Lp0t_a_ng0:
	v_cvt_pk_bf16_f32 v96, v64, v65
	v_cvt_pk_bf16_f32 v97, v66, v67
	v_cvt_pk_bf16_f32 v98, v68, v69
	v_cvt_pk_bf16_f32 v99, v70, v71
	global_store_dwordx4 v8, v[96:99], s[90:91]
	s_add_u32 s90, s90, s92
	s_addc_u32 s91, s91, 0
	s_cmp_eq_u32 s93, 0
	s_waitcnt lgkmcnt(8)
	s_cbranch_scc1 .Lp0t_a_ng1
	v_mul_f32_e32 v72, v72, v18
	v_mul_f32_e32 v73, v73, v19
	v_mul_f32_e32 v74, v74, v20
	v_mul_f32_e32 v75, v75, v21
	v_mul_f32_e32 v76, v76, v22
	v_mul_f32_e32 v77, v77, v23
	v_mul_f32_e32 v78, v78, v24
	v_mul_f32_e32 v79, v79, v25
.Lp0t_a_ng1:
	v_cvt_pk_bf16_f32 v100, v72, v73
	v_cvt_pk_bf16_f32 v101, v74, v75
	v_cvt_pk_bf16_f32 v102, v76, v77
	v_cvt_pk_bf16_f32 v103, v78, v79
	global_store_dwordx4 v8, v[100:103], s[90:91]
	s_add_u32 s90, s90, s92
	s_addc_u32 s91, s91, 0
	s_cmp_eq_u32 s93, 0
	s_waitcnt lgkmcnt(4)
	s_cbranch_scc1 .Lp0t_a_ng2
	v_mul_f32_e32 v80, v80, v18
	v_mul_f32_e32 v81, v81, v19
	v_mul_f32_e32 v82, v82, v20
	v_mul_f32_e32 v83, v83, v21
	v_mul_f32_e32 v84, v84, v22
	v_mul_f32_e32 v85, v85, v23
	v_mul_f32_e32 v86, v86, v24
	v_mul_f32_e32 v87, v87, v25
.Lp0t_a_ng2:
	v_cvt_pk_bf16_f32 v96, v80, v81
	v_cvt_pk_bf16_f32 v97, v82, v83
	v_cvt_pk_bf16_f32 v98, v84, v85
	v_cvt_pk_bf16_f32 v99, v86, v87
	global_store_dwordx4 v8, v[96:99], s[90:91]
	s_add_u32 s90, s90, s92
	s_addc_u32 s91, s91, 0
	s_cmp_eq_u32 s93, 0
	s_waitcnt lgkmcnt(0)
	s_cbranch_scc1 .Lp0t_a_ng3
	v_mul_f32_e32 v88, v88, v18
	v_mul_f32_e32 v89, v89, v19
	v_mul_f32_e32 v90, v90, v20
	v_mul_f32_e32 v91, v91, v21
	v_mul_f32_e32 v92, v92, v22
	v_mul_f32_e32 v93, v93, v23
	v_mul_f32_e32 v94, v94, v24
	v_mul_f32_e32 v95, v95, v25
.Lp0t_a_ng3:
	v_cvt_pk_bf16_f32 v100, v88, v89
	v_cvt_pk_bf16_f32 v101, v90, v91
	v_cvt_pk_bf16_f32 v102, v92, v93
	v_cvt_pk_bf16_f32 v103, v94, v95
	global_store_dwordx4 v8, v[100:103], s[90:91]
	s_waitcnt vmcnt(4)
	s_branch .Lp0t_write

.Lp0t_write:
	s_mov_b64 s[90:91], s[88:89]
	s_mov_b32 s92, s84
	s_mov_b32 s93, s63
	v_mov_b32_e32 v8, v7
	v_mov_b32_e32 v18, v10
	v_mov_b32_e32 v19, v11
	v_mov_b32_e32 v20, v12
	v_mov_b32_e32 v21, v13
	v_mov_b32_e32 v22, v14
	v_mov_b32_e32 v23, v15
	v_mov_b32_e32 v24, v16
	v_mov_b32_e32 v25, v17
	ds_write_b32 v4, v32
	ds_write_b32 v4, v33 offset:264
	ds_write_b32 v4, v34 offset:528
	ds_write_b32 v4, v35 offset:792
	ds_write_b32 v4, v36 offset:1056
	ds_write_b32 v4, v37 offset:1320
	ds_write_b32 v4, v38 offset:1584
	ds_write_b32 v4, v39 offset:1848
	ds_write_b32 v4, v40 offset:2112
	ds_write_b32 v4, v41 offset:2376
	ds_write_b32 v4, v42 offset:2640
	ds_write_b32 v4, v43 offset:2904
	ds_write_b32 v4, v44 offset:3168
	ds_write_b32 v4, v45 offset:3432
	ds_write_b32 v4, v46 offset:3696
	ds_write_b32 v4, v47 offset:3960
	ds_write_b32 v4, v48 offset:4224
	ds_write_b32 v4, v49 offset:4488
	ds_write_b32 v4, v50 offset:4752
	ds_write_b32 v4, v51 offset:5016
	ds_write_b32 v4, v52 offset:5280
	ds_write_b32 v4, v53 offset:5544
	ds_write_b32 v4, v54 offset:5808
	ds_write_b32 v4, v55 offset:6072
	ds_write_b32 v4, v56 offset:6336
	ds_write_b32 v4, v57 offset:6600
	ds_write_b32 v4, v58 offset:6864
	ds_write_b32 v4, v59 offset:7128
	ds_write_b32 v4, v60 offset:7392
	ds_write_b32 v4, v61 offset:7656
	ds_write_b32 v4, v62 offset:7920
	ds_write_b32 v4, v63 offset:8184
	s_waitcnt lgkmcnt(0)
	s_mov_b32 s87, 1
	s_add_u32 s7, s7, s6
	s_cmp_lt_u32 s7, 23488
	s_cbranch_scc1 .Lp0t_top
	ds_read2_b32 v[64:65], v5 offset0:0 offset1:33
	ds_read2_b32 v[66:67], v5 offset0:66 offset1:99
	ds_read2_b32 v[68:69], v5 offset0:132 offset1:165
	ds_read2_b32 v[70:71], v5 offset0:198 offset1:231
	ds_read2_b32 v[72:73], v5 offset0:8 offset1:41
	ds_read2_b32 v[74:75], v5 offset0:74 offset1:107
	ds_read2_b32 v[76:77], v5 offset0:140 offset1:173
	ds_read2_b32 v[78:79], v5 offset0:206 offset1:239
	ds_read2_b32 v[80:81], v5 offset0:16 offset1:49
	ds_read2_b32 v[82:83], v5 offset0:82 offset1:115
	ds_read2_b32 v[84:85], v5 offset0:148 offset1:181
	ds_read2_b32 v[86:87], v5 offset0:214 offset1:247
	ds_read2_b32 v[88:89], v5 offset0:24 offset1:57
	ds_read2_b32 v[90:91], v5 offset0:90 offset1:123
	ds_read2_b32 v[92:93], v5 offset0:156 offset1:189
	ds_read2_b32 v[94:95], v5 offset0:222 offset1:255
	s_cmp_eq_u32 s93, 0
	s_waitcnt lgkmcnt(12)
	s_cbranch_scc1 .Lp0t_b_ng0
	v_mul_f32_e32 v64, v64, v18
	v_mul_f32_e32 v65, v65, v19
	v_mul_f32_e32 v66, v66, v20
	v_mul_f32_e32 v67, v67, v21
	v_mul_f32_e32 v68, v68, v22
	v_mul_f32_e32 v69, v69, v23
	v_mul_f32_e32 v70, v70, v24
	v_mul_f32_e32 v71, v71, v25

.Lp0t_b_ng3:
	v_cvt_pk_bf16_f32 v100, v88, v89
	v_cvt_pk_bf16_f32 v101, v90, v91
	v_cvt_pk_bf16_f32 v102, v92, v93
	v_cvt_pk_bf16_f32 v103, v94, v95
	global_store_dwordx4 v8, v[100:103], s[90:91]
